# hyena head-norm: the four tile loads per thread issued together instead of load-wait-write per row group
# speedup vs baseline: 1.0079x; 1.0068x over previous
; __device__ __forceinline__ void hy_headnorm_unit(KP p, int u, float* sm, int tid) {
;     ...
;   for (int i = tid; i < 128 * 16; i += NTH) { const int c = i >> 4, t4 = (i & 15) << 2; float v[4]; unpack4(*(const u32x2*)(Z2 + (size_t)c * SEQ + t4), v); float* d = sm + c * 65 + t4; d[0] = v[0]; d[1] = v[1]; d[2] = v[2]; d[3] = v[3]; }
.LBB0_92:
	s_lshl_b32 s2, s20, 6
	s_and_b32 s21, s2, 0x3fc0
	s_ashr_i32 s2, s20, 1
	s_and_b32 s12, s2, 0xffffff80
	s_ashr_i32 s13, s12, 31
	s_and_saveexec_b64 s[2:3], vcc
	s_movk_i32 s22, 0x5ff
	s_cbranch_execz .LBB0_95
	s_lshl_b64 s[8:9], s[12:13], 15
	s_add_u32 s8, s16, s8
	s_addc_u32 s9, s17, s9
	s_lshl_b32 s10, s21, 1
	s_add_u32 s10, s8, s10
	s_addc_u32 s11, s9, 0
	s_mov_b64 s[14:15], 0
	v_mov_b32_e32 v5, v1
	v_mov_b32_e32 v6, v146
	v_ashrrev_i32_e32 v8, 4, v6
	v_ashrrev_i32_e32 v9, 31, v8
	v_and_b32_e32 v7, 60, v5
	v_lshlrev_b64 v[18:19], 15, v[8:9]
	v_lshlrev_b32_e32 v138, 1, v7
	v_lshl_add_u64 v[18:19], s[10:11], 0, v[18:19]
	v_lshl_add_u64 v[18:19], v[18:19], 0, v[138:139]
	s_mov_b64 s[8:9], 0x100000
	global_load_dwordx2 v[10:11], v[18:19], off
	v_lshl_add_u64 v[18:19], v[18:19], 0, s[8:9]
	global_load_dwordx2 v[12:13], v[18:19], off
	v_lshl_add_u64 v[18:19], v[18:19], 0, s[8:9]
	global_load_dwordx2 v[14:15], v[18:19], off
	v_lshl_add_u64 v[18:19], v[18:19], 0, s[8:9]
	global_load_dwordx2 v[16:17], v[18:19], off
	v_mul_lo_u32 v8, v8, s95
	v_lshlrev_b32_e32 v7, 2, v7
	v_add3_u32 v7, 0, v8, v7
	s_waitcnt vmcnt(3)
	v_lshlrev_b32_e32 v5, 16, v10
	v_and_b32_e32 v6, 0xffff0000, v10
	v_lshlrev_b32_e32 v8, 16, v11
	v_and_b32_e32 v9, 0xffff0000, v11
	ds_write2_b32 v7, v5, v6 offset1:1
	ds_write2_b32 v7, v8, v9 offset0:2 offset1:3
	v_add_u32_e32 v7, 0x2080, v7
	s_waitcnt vmcnt(2)
	v_lshlrev_b32_e32 v5, 16, v12
	v_and_b32_e32 v6, 0xffff0000, v12
	v_lshlrev_b32_e32 v8, 16, v13
	v_and_b32_e32 v9, 0xffff0000, v13
	ds_write2_b32 v7, v5, v6 offset1:1
	ds_write2_b32 v7, v8, v9 offset0:2 offset1:3
	v_add_u32_e32 v7, 0x2080, v7
	s_waitcnt vmcnt(1)
	v_lshlrev_b32_e32 v5, 16, v14
	v_and_b32_e32 v6, 0xffff0000, v14
	v_lshlrev_b32_e32 v8, 16, v15
	v_and_b32_e32 v9, 0xffff0000, v15
	ds_write2_b32 v7, v5, v6 offset1:1
	ds_write2_b32 v7, v8, v9 offset0:2 offset1:3
	v_add_u32_e32 v7, 0x2080, v7
	s_waitcnt vmcnt(0)
	v_lshlrev_b32_e32 v5, 16, v16
	v_and_b32_e32 v6, 0xffff0000, v16
	v_lshlrev_b32_e32 v8, 16, v17
	v_and_b32_e32 v9, 0xffff0000, v17
	ds_write2_b32 v7, v5, v6 offset1:1
	ds_write2_b32 v7, v8, v9 offset0:2 offset1:3
